# hyena_ctx inner loops: contiguous filter layout in LDS (8 reads in flight, no per-term select), on top of fft loop rewrites
# speedup vs baseline: 1.0100x; 1.0037x over previous
; __device__ __forceinline__ void hyena_ctx(Frame& F, int l, int ch, LAS float* S, const LAS float* CT, bool wr = true) {
;     ...
;         if (F.tid < 256) hfl[n] = HFC[(size_t)(o * 1024 + ch) * CTXL + n]; else hbl[n] = HFC[(size_t)(o * 1024 + 512 + ch) * CTXL + n];
.LBB0_995:
	s_andn2_saveexec_b64 s[18:19], s[20:21]
	s_cbranch_execz .LBB0_997
	s_ashr_i32 s13, s12, 31
	s_lshl_b64 s[20:21], s[12:13], 10
	v_lshl_add_u64 v[8:9], v[6:7], 0, s[20:21]
	global_load_dword v8, v[8:9], off
	s_waitcnt vmcnt(0)
	ds_write_b32 v5, v8 offset:4096

; #define GAS __attribute__((address_space(1)))
; __device__ __forceinline__ void hyena_ctx(Frame& F, int l, int ch, LAS float* S, const LAS float* CT, bool wr = true) {
;     ...
;         for (int mI = 0; mI < CTXL; ++mI) { const int d = n - mI; y += zb[b * 256 + mI] * (d >= 0 ? hfl[d] : hbl[CTXL + d]); }
;         y += CT[12 + o] * zb[b * 256 + n];
;         const GAS float* hx = o == 0 ? hx1 : hx2; const int xo = o == 0 ? 512 : 1024;
;         const int xp = o == 0 ? 1 : 2; const float r = conv3(hx + b * CTXL, n, CTXL, CT[3 * xp], CT[3 * xp + 1], CT[3 * xp + 2], CT[9 + xp]) * y;
.LBB0_998:
	ds_read_b128 v[18:21], v10
	ds_read_b128 v[22:25], v10 offset:16
	v_add_u32_e32 v196, 0xfe4, v9
	ds_read_b32 v188, v196 offset:28
	ds_read_b32 v189, v196 offset:24
	ds_read_b32 v190, v196 offset:20
	ds_read_b32 v191, v196 offset:16
	ds_read_b32 v192, v196 offset:12
	ds_read_b32 v193, v196 offset:8
	ds_read_b32 v194, v196 offset:4
	ds_read_b32 v195, v196 offset:0
	v_add_u32_e32 v10, 32, v10
	v_subrev_u32_e32 v9, 32, v9
	v_add_u32_e32 v8, -8, v8
	s_add_i32 s5, s5, 8
	s_cmpk_eq_i32 s5, 0x107
	s_waitcnt lgkmcnt(0)
	v_fmac_f32_e32 v16, v18, v188
	v_fmac_f32_e32 v16, v19, v189
	v_fmac_f32_e32 v16, v20, v190
	v_fmac_f32_e32 v16, v21, v191
	v_fmac_f32_e32 v16, v22, v192
	v_fmac_f32_e32 v16, v23, v193
	v_fmac_f32_e32 v16, v24, v194
	v_fmac_f32_e32 v16, v25, v195
	s_cbranch_scc0 .LBB0_998
	s_add_i32 s18, s12, 0x400
	s_mul_i32 s13, s18, 0x20800
	s_mul_hi_i32 s5, s18, 0x20800
	s_add_u32 s20, s0, s13
	s_addc_u32 s21, s2, s5
	v_lshl_add_u64 v[8:9], v[2:3], 2, s[20:21]
	v_lshl_add_u64 v[12:13], v[8:9], 0, v[176:177]
	v_add_co_u32_e32 v8, vcc, 0x20000, v12
	s_mov_b64 s[20:21], 0x20000
	s_nop 0
	v_addc_co_u32_e32 v9, vcc, 0, v13, vcc
	global_load_dword v18, v[8:9], off
	v_mov_b32_e32 v8, s4
	ds_read_b64 v[10:11], v8 offset:16
	ds_read2_b32 v[8:9], v8 offset0:10 offset1:12
	ds_read_b32 v17, v15
	v_mov_b32_e32 v29, 0xfe4
	v_mov_b32_e32 v28, 0x7e4
	v_mov_b32_e32 v27, 0xfe8
	v_mov_b32_e32 v26, 0x7e8
	v_mov_b32_e32 v19, 0xfec
	v_lshl_add_u64 v[12:13], v[12:13], 0, s[20:21]
	s_waitcnt vmcnt(0) lgkmcnt(1)
	v_fma_f32 v8, v10, v18, v8
	s_and_saveexec_b64 s[20:21], s[8:9]
	s_cbranch_execz .LBB0_1001
	global_load_dword v18, v[12:13], off offset:-4
	s_add_i32 s5, s3, 0x2680c
	v_mov_b32_e32 v10, s5
	ds_read_b32 v10, v10
	s_waitcnt vmcnt(0) lgkmcnt(0)
	v_fmac_f32_e32 v8, v10, v18

; __device__ __forceinline__ void hyena_ctx(Frame& F, int l, int ch, LAS float* S, const LAS float* CT, bool wr = true) {
;     ...
;         if (F.tid < 256) hfl[n] = HFC[(size_t)(o * 1024 + ch) * CTXL + n]; else hbl[n] = HFC[(size_t)(o * 1024 + 512 + ch) * CTXL + n];
.LBB0_1005:
	s_andn2_saveexec_b64 s[20:21], s[20:21]
	s_cbranch_execz .LBB0_1007
	s_ashr_i32 s19, s18, 31
	s_lshl_b64 s[18:19], s[18:19], 10
	v_lshl_add_u64 v[8:9], v[6:7], 0, s[18:19]
	global_load_dword v8, v[8:9], off
	s_waitcnt vmcnt(0)
	ds_write_b32 v5, v8 offset:4096

; #define GAS __attribute__((address_space(1)))
; __device__ __forceinline__ void hyena_ctx(Frame& F, int l, int ch, LAS float* S, const LAS float* CT, bool wr = true) {
;     ...
;         for (int mI = 0; mI < CTXL; ++mI) { const int d = n - mI; y += zb[b * 256 + mI] * (d >= 0 ? hfl[d] : hbl[CTXL + d]); }
;         y += CT[12 + o] * zb[b * 256 + n];
;         const GAS float* hx = o == 0 ? hx1 : hx2; const int xo = o == 0 ? 512 : 1024;
;         const int xp = o == 0 ? 1 : 2; const float r = conv3(hx + b * CTXL, n, CTXL, CT[3 * xp], CT[3 * xp + 1], CT[3 * xp + 2], CT[9 + xp]) * y;
.LBB0_1008:
	ds_read_b128 v[18:21], v10
	ds_read_b128 v[22:25], v10 offset:16
	v_add_u32_e32 v196, 0xfe4, v9
	ds_read_b32 v188, v196 offset:28
	ds_read_b32 v189, v196 offset:24
	ds_read_b32 v190, v196 offset:20
	ds_read_b32 v191, v196 offset:16
	ds_read_b32 v192, v196 offset:12
	ds_read_b32 v193, v196 offset:8
	ds_read_b32 v194, v196 offset:4
	ds_read_b32 v195, v196 offset:0
	v_add_u32_e32 v10, 32, v10
	v_subrev_u32_e32 v9, 32, v9
	v_add_u32_e32 v8, -8, v8
	s_add_i32 s5, s5, 8
	s_cmpk_lg_i32 s5, 0x107
	s_waitcnt lgkmcnt(0)
	v_fmac_f32_e32 v16, v18, v188
	v_fmac_f32_e32 v16, v19, v189
	v_fmac_f32_e32 v16, v20, v190
	v_fmac_f32_e32 v16, v21, v191
	v_fmac_f32_e32 v16, v22, v192
	v_fmac_f32_e32 v16, v23, v193
	v_fmac_f32_e32 v16, v24, v194
	v_fmac_f32_e32 v16, v25, v195
	s_cbranch_scc1 .LBB0_1008
	v_mov_b32_e32 v10, s4
	s_add_i32 s4, s12, 0x600
	s_mul_hi_i32 s5, s4, 0x20800
	s_mul_i32 s4, s4, 0x20800
	s_add_u32 s4, s0, s4
	s_addc_u32 s5, s2, s5
	v_lshl_add_u64 v[12:13], v[2:3], 2, s[4:5]
	v_lshl_add_u64 v[18:19], v[12:13], 0, v[176:177]
	s_mov_b64 s[4:5], 0x20000
	v_lshl_add_u64 v[12:13], v[18:19], 0, s[4:5]
	v_add_co_u32_e32 v18, vcc, 0x20000, v18
	ds_read2_b32 v[8:9], v10 offset0:11 offset1:13
	ds_read_b32 v17, v15
	v_addc_co_u32_e32 v19, vcc, 0, v19, vcc
	global_load_dword v18, v[18:19], off
	ds_read2_b32 v[10:11], v10 offset0:7 offset1:8
	s_waitcnt vmcnt(0) lgkmcnt(0)
	v_fma_f32 v8, v10, v18, v8
	s_and_saveexec_b64 s[18:19], s[8:9]
	s_cbranch_execz .LBB0_1011
	global_load_dword v18, v[12:13], off offset:-4
	s_add_i32 s3, s3, 0x26818
	v_mov_b32_e32 v10, s3
	ds_read_b32 v10, v10
	s_waitcnt vmcnt(0) lgkmcnt(0)
	v_fmac_f32_e32 v8, v10, v18
